# B (GQA) loop: PV MFMA operands swapped -> O^T accumulators (one q row per lane); per-lane rescale, epilogue normalises per lane and stores rows directly via permlane32_swap + dwordx4 (no LDS transposi
# baseline (speedup 1.0000x reference)
; template <int DQK, int MODE>
; DI void attn_body(const AttnArgs& a, char* lds) {
;     ...
;     auto finishSM = [&](f32x16& p0, f32x16& p1, float alpha, bf16x8& pa0, bf16x8& pa1, bf16x8& pa2, bf16x8& pa3) {
; #pragma unroll
;         for (int r = 0; r < 16; ++r) p1[r] = __builtin_amdgcn_exp2f(p1[r]);
;         float ps = 0;
; #pragma unroll
;         for (int r = 0; r < 16; ++r) ps += p0[r];
; #pragma unroll
;         for (int r = 0; r < 16; ++r) ps += p1[r];
;         { auto rr = __builtin_amdgcn_permlane32_swap(__float_as_uint(ps), __float_as_uint(ps), false, false);
;           ps = __uint_as_float(rr[0]) + __uint_as_float(rr[1]); }
;         l_reg = l_reg * alpha + ps;
;     ...
;         PK4(p0, 0, pa0); PK4(p0, 8, pa1); PK4(p1, 0, pa2); PK4(p1, 8, pa3);
.Lstg_b_nov:
	v_exp_f32_e32 v81, v82
	v_exp_f32_e32 v159, v83
	v_exp_f32_e32 v84, v84
	v_exp_f32_e32 v85, v85
	v_exp_f32_e32 v86, v86
	v_exp_f32_e32 v160, v70
	v_add_f32_e32 v70, 0, v81
	v_exp_f32_e32 v87, v87
	v_add_f32_e32 v70, v159, v70
	v_exp_f32_e32 v88, v88
	v_add_f32_e32 v70, v84, v70
	v_exp_f32_e32 v89, v89
	v_add_f32_e32 v70, v85, v70
	v_exp_f32_e32 v90, v90
	v_add_f32_e32 v70, v86, v70
	v_exp_f32_e32 v91, v91
	v_add_f32_e32 v70, v87, v70
	v_exp_f32_e32 v92, v92
	v_add_f32_e32 v70, v88, v70
	v_exp_f32_e32 v93, v93
	v_add_f32_e32 v70, v89, v70
	v_exp_f32_e32 v94, v94
	v_add_f32_e32 v70, v90, v70
	v_exp_f32_e32 v95, v95
	v_add_f32_e32 v70, v91, v70
	v_exp_f32_e32 v96, v96
	v_add_f32_e32 v70, v92, v70
	v_exp_f32_e32 v97, v97
	v_add_f32_e32 v70, v93, v70
	v_exp_f32_e32 v66, v66
	v_add_f32_e32 v70, v94, v70
	v_exp_f32_e32 v67, v67
	v_add_f32_e32 v70, v95, v70
	v_exp_f32_e32 v68, v68
	v_add_f32_e32 v70, v96, v70
	v_exp_f32_e32 v69, v69
	v_add_f32_e32 v70, v97, v70
	v_add_f32_e32 v70, v66, v70
	v_exp_f32_e32 v161, v71
	v_add_f32_e32 v70, v67, v70
	v_exp_f32_e32 v162, v72
	v_add_f32_e32 v70, v68, v70
	v_exp_f32_e32 v73, v73
	v_add_f32_e32 v70, v69, v70
	v_exp_f32_e32 v163, v74
	v_add_f32_e32 v70, v160, v70
	v_exp_f32_e32 v164, v75
	v_add_f32_e32 v70, v161, v70
	v_exp_f32_e32 v165, v76
	v_add_f32_e32 v70, v162, v70
	v_exp_f32_e32 v166, v77
	v_add_f32_e32 v70, v73, v70
	v_exp_f32_e32 v167, v78
	v_add_f32_e32 v70, v163, v70
	v_exp_f32_e32 v168, v79
	v_add_f32_e32 v70, v164, v70
	v_exp_f32_e32 v169, v80
	v_add_f32_e32 v70, v165, v70
	v_exp_f32_e32 v158, v158
	v_add_f32_e32 v70, v166, v70
	v_add_f32_e32 v70, v167, v70
	v_add_f32_e32 v70, v168, v70
	v_add_f32_e32 v70, v169, v70
	v_add_f32_e32 v82, v158, v70
	v_mov_b32_e32 v83, v82
	v_cvt_pk_bf16_f32 v78, v81, v159
	v_cvt_pk_bf16_f32 v79, v84, v85
	v_cvt_pk_bf16_f32 v80, v86, v87
	v_cvt_pk_bf16_f32 v81, v88, v89
	v_cvt_pk_bf16_f32 v74, v90, v91
	v_cvt_pk_bf16_f32 v75, v92, v93
	v_cvt_pk_bf16_f32 v76, v94, v95
	v_cvt_pk_bf16_f32 v77, v96, v97
	v_cvt_pk_bf16_f32 v70, v66, v67
	v_cvt_pk_bf16_f32 v71, v68, v69
	v_cvt_pk_bf16_f32 v72, v160, v161
	v_cvt_pk_bf16_f32 v73, v162, v73
	v_cvt_pk_bf16_f32 v66, v163, v164
	v_cvt_pk_bf16_f32 v67, v165, v166
	v_cvt_pk_bf16_f32 v68, v167, v168
	v_cvt_pk_bf16_f32 v69, v169, v158
	s_nop 1
	v_permlane32_swap_b32_e32 v82, v83
	s_cmp_eq_u32 s32, 0
	s_cbranch_scc1 .LBB0_815
	v_mul_f32_e32 v2, v157, v2
	v_mul_f32_e32 v3, v157, v3
	v_mul_f32_e32 v4, v157, v4
	v_mul_f32_e32 v5, v157, v5
	v_mul_f32_e32 v6, v157, v6
	v_mul_f32_e32 v7, v157, v7
	v_mul_f32_e32 v8, v157, v8
	v_mul_f32_e32 v9, v157, v9
	v_mul_f32_e32 v10, v157, v10
	v_mul_f32_e32 v11, v157, v11
	v_mul_f32_e32 v12, v157, v12
	v_mul_f32_e32 v13, v157, v13
	v_mul_f32_e32 v14, v157, v14
	v_mul_f32_e32 v15, v157, v15
	v_mul_f32_e32 v16, v157, v16
	v_mul_f32_e32 v17, v157, v17
	v_mul_f32_e32 v50, v157, v50
	v_mul_f32_e32 v51, v157, v51
	v_mul_f32_e32 v52, v157, v52
	v_mul_f32_e32 v53, v157, v53
	v_mul_f32_e32 v54, v157, v54
	v_mul_f32_e32 v55, v157, v55
	v_mul_f32_e32 v56, v157, v56
	v_mul_f32_e32 v57, v157, v57
	v_mul_f32_e32 v58, v157, v58
	v_mul_f32_e32 v59, v157, v59
	v_mul_f32_e32 v60, v157, v60
	v_mul_f32_e32 v61, v157, v61
	v_mul_f32_e32 v62, v157, v62
	v_mul_f32_e32 v63, v157, v63
	v_mul_f32_e32 v64, v157, v64
	v_mul_f32_e32 v65, v157, v65
	v_mul_f32_e32 v34, v157, v34
	v_mul_f32_e32 v35, v157, v35
	v_mul_f32_e32 v36, v157, v36
	v_mul_f32_e32 v37, v157, v37
	v_mul_f32_e32 v38, v157, v38
	v_mul_f32_e32 v39, v157, v39
	v_mul_f32_e32 v40, v157, v40
	v_mul_f32_e32 v41, v157, v41
	v_mul_f32_e32 v42, v157, v42
	v_mul_f32_e32 v43, v157, v43
	v_mul_f32_e32 v44, v157, v44
	v_mul_f32_e32 v45, v157, v45
	v_mul_f32_e32 v46, v157, v46
	v_mul_f32_e32 v47, v157, v47
	v_mul_f32_e32 v48, v157, v48
	v_mul_f32_e32 v49, v157, v49
	v_mul_f32_e32 v18, v157, v18
	v_mul_f32_e32 v19, v157, v19
	v_mul_f32_e32 v20, v157, v20
	v_mul_f32_e32 v21, v157, v21
	v_mul_f32_e32 v22, v157, v22
	v_mul_f32_e32 v23, v157, v23
	v_mul_f32_e32 v24, v157, v24
	v_mul_f32_e32 v25, v157, v25
	v_mul_f32_e32 v26, v157, v26
	v_mul_f32_e32 v27, v157, v27
	v_mul_f32_e32 v28, v157, v28
	v_mul_f32_e32 v29, v157, v29
	v_mul_f32_e32 v30, v157, v30
	v_mul_f32_e32 v31, v157, v31
	v_mul_f32_e32 v32, v157, v32
	v_mul_f32_e32 v33, v157, v33
	v_mul_f32_e32 v156, v156, v157
; #define SBAR() __builtin_amdgcn_sched_barrier(0)
; template <int N> DI void wait_lgkm() { asm volatile("s_waitcnt lgkmcnt(%0)" :: "i"(N) : "memory"); }
; #define RESC(al) do { if (__any((al) < 1.f)) { if (hi == 0) al_l[r32] = (al); asm volatile("s_waitcnt lgkmcnt(0)" ::: "memory"); \
;     _Pragma("unroll") for (int d = 0; d < 4; ++d) _Pragma("unroll") for (int r = 0; r < 16; ++r) o[d][r] *= al_l[crow(r, hi)]; } } while (0)
; #define DMA(buf, k0) do { _Pragma("unroll") for (int _i = 0; _i < NI; ++_i) { \
;         char* _d = (_i < 2) ? V_lds + (buf) * SHM_V + (wu + 8 * _i) * 1024 : K_lds + (buf) * SHM_K + (wu + 8 * _i - 16) * 1024; \
;         __builtin_amdgcn_global_load_lds((const unsigned*)(sp[_i] + (size_t)(k0) * sld[_i]), (LAS unsigned*)_d, 16, 0, 0); } } while (0)
; DI void pv_mm(f32x16* o, const s16x4* f, bf16x8 pa) {
;     ...
;     o[0] = __builtin_amdgcn_mfma_f32_32x32x16_bf16(pa, PK(f[0], f[1]), o[0], 0, 0, 0);
;     o[1] = __builtin_amdgcn_mfma_f32_32x32x16_bf16(pa, PK(f[2], f[3]), o[1], 0, 0, 0);
;     o[2] = __builtin_amdgcn_mfma_f32_32x32x16_bf16(pa, PK(f[4], f[5]), o[2], 0, 0, 0);
;     o[3] = __builtin_amdgcn_mfma_f32_32x32x16_bf16(pa, PK(f[6], f[7]), o[3], 0, 0, 0);
;     ...
; }
; DI void pv_d0(f32x16* o, int vb, bf16x8 pa0, bf16x8 pa1, bf16x8 pa2, bf16x8 pa3) {
;     s16x4 fa[8], fb[8];
;     v_rd8<0>(fa, vb);
;     v_rd8<1>(fb, vb); wait_lgkm<8>(); SBAR(); pv_mm(o, fa, pa0);
;     v_rd8<2>(fa, vb); wait_lgkm<8>(); SBAR(); pv_mm(o, fb, pa1);
;     v_rd8<3>(fb, vb); wait_lgkm<8>(); SBAR(); pv_mm(o, fa, pa2);
;     wait_lgkm<0>(); SBAR(); pv_mm(o, fb, pa3);
; template <int DQK, int MODE>
; DI void attn_body(const AttnArgs& a, char* lds) {
;     ...
;     for (int j = 0; j < NT; ++j) {
;         const int cur = j & 1;
;         if (j + 1 < NT) DMA(cur ^ 1, (j + 1) * 64);
;         f32x16 p0, p1; float mn, alpha;
;         qkt(p0, p1, cur * SHM_K);
;         partialSM(p0, p1, mn, alpha, j * 64);
;         finishSM(p0, p1, alpha, pa0, pa1, pa2, pa3);
;         RESC(alpha);
;         pv_d0(o, vb0 + cur * SHM_V, pa0, pa1, pa2, pa3);
;         asm volatile("s_waitcnt vmcnt(0)" ::: "memory");
;         __syncthreads();
;     }
.LBB0_815:
	v_add_f32_e32 v82, v82, v83
	v_add_u32_e32 v83, s49, v154
	ds_read_b64_tr_b16 v[84:85], v83 offset:0
	ds_read_b64_tr_b16 v[86:87], v83 offset:0x800
	ds_read_b64_tr_b16 v[88:89], v83 offset:0x200
	ds_read_b64_tr_b16 v[90:91], v83 offset:0xa00
	ds_read_b64_tr_b16 v[92:93], v83 offset:0x400
	ds_read_b64_tr_b16 v[94:95], v83 offset:0xc00
	v_add_f32_e32 v82, v82, v156
	ds_read_b64_tr_b16 v[156:157], v83 offset:0x600
	ds_read_b64_tr_b16 v[158:159], v83 offset:0xe00
	ds_read_b64_tr_b16 v[160:161], v83 offset:0x1000
	ds_read_b64_tr_b16 v[162:163], v83 offset:0x1800
	ds_read_b64_tr_b16 v[164:165], v83 offset:0x1200
	ds_read_b64_tr_b16 v[166:167], v83 offset:0x1a00
	ds_read_b64_tr_b16 v[168:169], v83 offset:0x1400
	ds_read_b64_tr_b16 v[170:171], v83 offset:0x1c00
	ds_read_b64_tr_b16 v[172:173], v83 offset:0x1600
	ds_read_b64_tr_b16 v[174:175], v83 offset:0x1e00
	s_waitcnt lgkmcnt(8)
	v_mfma_f32_32x32x16_bf16 v[2:17], v[84:87], v[78:81], v[2:17]
	v_mfma_f32_32x32x16_bf16 v[50:65], v[88:91], v[78:81], v[50:65]
	v_mfma_f32_32x32x16_bf16 v[34:49], v[92:95], v[78:81], v[34:49]
	v_mfma_f32_32x32x16_bf16 v[18:33], v[156:159], v[78:81], v[18:33]
	ds_read_b64_tr_b16 v[78:79], v83 offset:0x2000
	ds_read_b64_tr_b16 v[80:81], v83 offset:0x2800
	ds_read_b64_tr_b16 v[84:85], v83 offset:0x2200
	ds_read_b64_tr_b16 v[86:87], v83 offset:0x2a00
	ds_read_b64_tr_b16 v[88:89], v83 offset:0x2400
	ds_read_b64_tr_b16 v[90:91], v83 offset:0x2c00
	ds_read_b64_tr_b16 v[92:93], v83 offset:0x2600
	ds_read_b64_tr_b16 v[94:95], v83 offset:0x2e00
	s_waitcnt lgkmcnt(8)
	v_mfma_f32_32x32x16_bf16 v[2:17], v[160:163], v[74:77], v[2:17]
	v_mfma_f32_32x32x16_bf16 v[50:65], v[164:167], v[74:77], v[50:65]
	v_mfma_f32_32x32x16_bf16 v[34:49], v[168:171], v[74:77], v[34:49]
	v_mfma_f32_32x32x16_bf16 v[18:33], v[172:175], v[74:77], v[18:33]
	ds_read_b64_tr_b16 v[74:75], v83 offset:0x3000
	ds_read_b64_tr_b16 v[76:77], v83 offset:0x3800
	ds_read_b64_tr_b16 v[156:157], v83 offset:0x3200
	ds_read_b64_tr_b16 v[158:159], v83 offset:0x3a00
	ds_read_b64_tr_b16 v[160:161], v83 offset:0x3400
	ds_read_b64_tr_b16 v[162:163], v83 offset:0x3c00
	ds_read_b64_tr_b16 v[164:165], v83 offset:0x3600
	ds_read_b64_tr_b16 v[166:167], v83 offset:0x3e00
	s_waitcnt lgkmcnt(8)
	v_mfma_f32_32x32x16_bf16 v[2:17], v[78:81], v[70:73], v[2:17]
	s_waitcnt lgkmcnt(0)
	v_mfma_f32_32x32x16_bf16 v[50:65], v[84:87], v[70:73], v[50:65]
	v_mfma_f32_32x32x16_bf16 v[34:49], v[88:91], v[70:73], v[34:49]
	v_mfma_f32_32x32x16_bf16 v[18:33], v[92:95], v[70:73], v[18:33]
	v_mfma_f32_32x32x16_bf16 v[2:17], v[74:77], v[66:69], v[2:17]
	s_waitcnt vmcnt(0)
	s_add_i32 s37, s37, 64
	s_add_u32 s89, s89, 0x170000
	s_addc_u32 s90, s90, 0
	s_cmp_eq_u32 s47, s36
	s_waitcnt vmcnt(0) lgkmcnt(0)
	s_barrier
	v_mfma_f32_32x32x16_bf16 v[50:65], v[156:159], v[66:69], v[50:65]
	v_mfma_f32_32x32x16_bf16 v[34:49], v[160:163], v[66:69], v[34:49]
	v_mfma_f32_32x32x16_bf16 v[18:33], v[164:167], v[66:69], v[18:33]
	s_cbranch_scc1 .LBB0_817
	v_mov_b32_e32 v156, v82
	s_branch .LBB0_807

;     DI void* gp(int i) const { return (void*)(__attribute__((address_space(1))) void*)ld(i); }
; DI unsigned short f2bf(float f) { return (unsigned short)(cvtpk(f, f) & 0xffffu); }
; DI int crow(int r, int hi) { return (r & 3) + 8 * (r >> 2) + 4 * hi; }
; template <int DQK, int MODE>
; DI void attn_body(const AttnArgs& a, char* lds) {
;     ...
;     if (hi == 0) li_l[r32] = l_reg; asm volatile("s_waitcnt lgkmcnt(0)" ::: "memory");
;     char* ost = lds + wid * 8192;
; #pragma unroll
;     for (int r = 0; r < 16; ++r) { const int orow = crow(r, hi); const float rl = __builtin_amdgcn_rcpf(li_l[orow]);
; #pragma unroll
;         for (int d0 = 0; d0 < 4; ++d0) *(bf16_t*)(ost + orow * 256 + (d0 * 32 + r32) * 2) = f2bf(o[d0][r] * rl); }
;     asm volatile("s_waitcnt lgkmcnt(0)" ::: "memory");
;     {
;         const int row = lane >> 1, hf = lane & 1;
;         bf16_t* gp = a.O + (size_t)(wid * 32 + row) * a.ldo + hf * 64;
;         const char* sp = ost + row * 256 + hf * 128;
;         if (MODE != 1 || a.map == 0) {
; #pragma unroll
;             for (int c = 0; c < 8; ++c) *(u32x4*)(gp + c * 8) = *(const u32x4*)(sp + c * 16);
.Lstg_b_epi:
	s_nop 7
	v_rcp_f32_e32 v67, v82
	s_mulk_i32 s16, 0x1800
	s_add_u32 s4, s15, s16
	s_addc_u32 s5, s14, 0
	s_lshl_b32 s16, s17, 1
	s_add_u32 s4, s4, s16
	s_addc_u32 s5, s5, 0
	s_add_u32 s4, s4, 0x1fc80800
	s_addc_u32 s5, s5, 0
	v_lshl_or_b32 v66, v141, 5, v143
	v_lshlrev_b32_e32 v68, 4, v142
	v_mul_u32_u24_e32 v66, 0x1800, v66
	v_add_u32_e32 v66, v66, v68
	v_mul_f32_e32 v2, v67, v2
	v_mul_f32_e32 v3, v67, v3
	v_mul_f32_e32 v4, v67, v4
	v_mul_f32_e32 v5, v67, v5
	v_mul_f32_e32 v6, v67, v6
	v_mul_f32_e32 v7, v67, v7
	v_mul_f32_e32 v8, v67, v8
	v_mul_f32_e32 v9, v67, v9
	v_mul_f32_e32 v10, v67, v10
	v_mul_f32_e32 v11, v67, v11
	v_mul_f32_e32 v12, v67, v12
	v_mul_f32_e32 v13, v67, v13
	v_mul_f32_e32 v14, v67, v14
	v_mul_f32_e32 v15, v67, v15
	v_mul_f32_e32 v16, v67, v16
	v_mul_f32_e32 v17, v67, v17
	v_cvt_pk_bf16_f32 v2, v2, v3
	v_cvt_pk_bf16_f32 v3, v4, v5
	v_cvt_pk_bf16_f32 v4, v6, v7
	v_cvt_pk_bf16_f32 v5, v8, v9
	v_cvt_pk_bf16_f32 v6, v10, v11
	v_cvt_pk_bf16_f32 v7, v12, v13
	v_cvt_pk_bf16_f32 v8, v14, v15
	v_cvt_pk_bf16_f32 v9, v16, v17
	s_nop 1
	v_permlane32_swap_b32_e32 v2, v4
	v_permlane32_swap_b32_e32 v3, v5
	v_permlane32_swap_b32_e32 v6, v8
	v_permlane32_swap_b32_e32 v7, v9
	global_store_dwordx4 v66, v[2:5], s[4:5]
	global_store_dwordx4 v66, v[6:9], s[4:5] offset:32
	v_mul_f32_e32 v50, v67, v50
	v_mul_f32_e32 v51, v67, v51
	v_mul_f32_e32 v52, v67, v52
	v_mul_f32_e32 v53, v67, v53
	v_mul_f32_e32 v54, v67, v54
	v_mul_f32_e32 v55, v67, v55
	v_mul_f32_e32 v56, v67, v56
	v_mul_f32_e32 v57, v67, v57
	v_mul_f32_e32 v58, v67, v58
	v_mul_f32_e32 v59, v67, v59
	v_mul_f32_e32 v60, v67, v60
	v_mul_f32_e32 v61, v67, v61
	v_mul_f32_e32 v62, v67, v62
	v_mul_f32_e32 v63, v67, v63
	v_mul_f32_e32 v64, v67, v64
	v_mul_f32_e32 v65, v67, v65
	v_cvt_pk_bf16_f32 v50, v50, v51
	v_cvt_pk_bf16_f32 v51, v52, v53
	v_cvt_pk_bf16_f32 v52, v54, v55
	v_cvt_pk_bf16_f32 v53, v56, v57
	v_cvt_pk_bf16_f32 v54, v58, v59
	v_cvt_pk_bf16_f32 v55, v60, v61
	v_cvt_pk_bf16_f32 v56, v62, v63
	v_cvt_pk_bf16_f32 v57, v64, v65
	s_nop 1
	v_permlane32_swap_b32_e32 v50, v52
	v_permlane32_swap_b32_e32 v51, v53
	v_permlane32_swap_b32_e32 v54, v56
	v_permlane32_swap_b32_e32 v55, v57
	global_store_dwordx4 v66, v[50:53], s[4:5] offset:64
	global_store_dwordx4 v66, v[54:57], s[4:5] offset:96
	v_mul_f32_e32 v34, v67, v34
	v_mul_f32_e32 v35, v67, v35
	v_mul_f32_e32 v36, v67, v36
	v_mul_f32_e32 v37, v67, v37
	v_mul_f32_e32 v38, v67, v38
	v_mul_f32_e32 v39, v67, v39
	v_mul_f32_e32 v40, v67, v40
	v_mul_f32_e32 v41, v67, v41
	v_mul_f32_e32 v42, v67, v42
	v_mul_f32_e32 v43, v67, v43
	v_mul_f32_e32 v44, v67, v44
	v_mul_f32_e32 v45, v67, v45
	v_mul_f32_e32 v46, v67, v46
	v_mul_f32_e32 v47, v67, v47
	v_mul_f32_e32 v48, v67, v48
	v_mul_f32_e32 v49, v67, v49
	v_cvt_pk_bf16_f32 v34, v34, v35
	v_cvt_pk_bf16_f32 v35, v36, v37
	v_cvt_pk_bf16_f32 v36, v38, v39
	v_cvt_pk_bf16_f32 v37, v40, v41
	v_cvt_pk_bf16_f32 v38, v42, v43
	v_cvt_pk_bf16_f32 v39, v44, v45
	v_cvt_pk_bf16_f32 v40, v46, v47
	v_cvt_pk_bf16_f32 v41, v48, v49
	s_nop 1
	v_permlane32_swap_b32_e32 v34, v36
	v_permlane32_swap_b32_e32 v35, v37
	v_permlane32_swap_b32_e32 v38, v40
	v_permlane32_swap_b32_e32 v39, v41
	global_store_dwordx4 v66, v[34:37], s[4:5] offset:128
	global_store_dwordx4 v66, v[38:41], s[4:5] offset:160
	v_mul_f32_e32 v18, v67, v18
	v_mul_f32_e32 v19, v67, v19
	v_mul_f32_e32 v20, v67, v20
	v_mul_f32_e32 v21, v67, v21
	v_mul_f32_e32 v22, v67, v22
	v_mul_f32_e32 v23, v67, v23
	v_mul_f32_e32 v24, v67, v24
	v_mul_f32_e32 v25, v67, v25
	v_mul_f32_e32 v26, v67, v26
	v_mul_f32_e32 v27, v67, v27
	v_mul_f32_e32 v28, v67, v28
	v_mul_f32_e32 v29, v67, v29
	v_mul_f32_e32 v30, v67, v30
	v_mul_f32_e32 v31, v67, v31
	v_mul_f32_e32 v32, v67, v32
	v_mul_f32_e32 v33, v67, v33
	v_cvt_pk_bf16_f32 v18, v18, v19
	v_cvt_pk_bf16_f32 v19, v20, v21
	v_cvt_pk_bf16_f32 v20, v22, v23
	v_cvt_pk_bf16_f32 v21, v24, v25
	v_cvt_pk_bf16_f32 v22, v26, v27
	v_cvt_pk_bf16_f32 v23, v28, v29
	v_cvt_pk_bf16_f32 v24, v30, v31
	v_cvt_pk_bf16_f32 v25, v32, v33
	s_nop 1
	v_permlane32_swap_b32_e32 v18, v20
	v_permlane32_swap_b32_e32 v19, v21
	v_permlane32_swap_b32_e32 v22, v24
	v_permlane32_swap_b32_e32 v23, v25
	global_store_dwordx4 v66, v[18:21], s[4:5] offset:192
	global_store_dwordx4 v66, v[22:25], s[4:5] offset:224
	s_mov_b64 s[4:5], 0
	s_branch .LBB0_797
